# wave-half stagger in the P2 diff loop: two barriers per step, waves 4-7 run half a step behind waves 0-3 (extra entry barrier matched at exit)
# baseline (speedup 1.0000x reference)
; #define ATT_WAITBAR_ALL() asm volatile("s_waitcnt vmcnt(0) lgkmcnt(0)\n\ts_barrier" ::: "memory")
; #define ATT_WAITBAR_ONE() do { if (DIFF) asm volatile("s_waitcnt vmcnt(4) lgkmcnt(0)\n\ts_barrier" ::: "memory"); else asm volatile("s_waitcnt vmcnt(3) lgkmcnt(0)\n\ts_barrier" ::: "memory"); } while (0)
; template <bool DIFF>
; __device__ __forceinline__ void attn_item(LAS unsigned char* lds, const bf16_t* Z, bf16_t* MIX, int b, int h, int t, float lam, float shift, const float* gain, int tid, int wid, int lane) {
;     ...
;     for (int kt = 0; kt < nkt; ++kt) {
;         const int bnx = (bcur == 2) ? 0 : bcur + 1, bn2 = (bnx == 2) ? 0 : bnx + 1;
;         const bool more2 = (kt + 2 < nkt);
;         if (more2) ATT_DMA(kt + 2, bn2);
;     ...
;         if (kt + 1 < nkt) { if (more2) ATT_WAITBAR_ONE(); else ATT_WAITBAR_ALL(); }
.Ldx_b0:
	s_barrier
	s_mov_b32 s15, 1
	s_cmp_lg_u32 s83, s70
	s_cbranch_scc0 .Ldx_loop
	s_barrier

; #define ATT_WAITBAR_ALL() asm volatile("s_waitcnt vmcnt(0) lgkmcnt(0)\n\ts_barrier" ::: "memory")
; #define ATT_WAITBAR_ONE() do { if (DIFF) asm volatile("s_waitcnt vmcnt(4) lgkmcnt(0)\n\ts_barrier" ::: "memory"); else asm volatile("s_waitcnt vmcnt(3) lgkmcnt(0)\n\ts_barrier" ::: "memory"); } while (0)
; #define ATT_KREAD(dst, c) do { _Pragma("unroll") for (int kb = 0; kb < 4; ++kb) _Pragma("unroll") for (int ds = 0; ds < 2; ++ds) \
;                 dst[kb * 2 + ds] = *(const LAS bf16x8*)(bp + (c) * 8192 + kb * 2048 + kfo + (((unsigned)(4 * ds + quad) ^ ksw) * 16)); } while (0)
; #define ATT_SMMA(sv, kf, c) do { _Pragma("unroll") for (int kb = 0; kb < 4; ++kb) { sv[kb] = (f32x4){sinit, sinit, sinit, sinit}; _Pragma("unroll") for (int ds = 0; ds < 2; ++ds) \
;                 sv[kb] = __builtin_amdgcn_mfma_f32_16x16x32_bf16(kf[kb * 2 + ds], qf[c][ds], sv[kb], 0, 0, 0); } } while (0)
; #define ATT_PV(c, lo_, hi_, eb0) do { _Pragma("unroll") for (int e = 0; e < 4; ++e) _Pragma("unroll") for (int ks = 0; ks < 2; ++ks) \
;                 O[c][(eb0) + e] = __builtin_amdgcn_mfma_f32_16x16x32_bf16(__builtin_shufflevector(lo_[e * 2 + ks], hi_[e * 2 + ks], 0, 1, 2, 3, 4, 5, 6, 7), P[c][ks], O[c][(eb0) + e], 0, 0, 0); } while (0)
; #define ATT_PVW(c, lo_, hi_, eb0) do { ATT_W4(12, lo_, hi_, 0); ATT_PV1(c, lo_, hi_, eb0, 0); ATT_W4(8, lo_, hi_, 1); ATT_PV1(c, lo_, hi_, eb0, 1); \
;                 ATT_W4(4, lo_, hi_, 2); ATT_PV1(c, lo_, hi_, eb0, 2); ATT_W4(0, lo_, hi_, 3); ATT_PV1(c, lo_, hi_, eb0, 3); } while (0)
; #define ATT_SB __builtin_amdgcn_sched_barrier(0)
; template <bool DIFF>
; __device__ __forceinline__ void attn_item(LAS unsigned char* lds, const bf16_t* Z, bf16_t* MIX, int b, int h, int t, float lam, float shift, const float* gain, int tid, int wid, int lane) {
;     ...
;             ATT_KREAD(kfA, 0); ATT_SB;
;             if (DIFF) { ATT_KREAD(kfB, NC - 1); ATT_SMMA(s0, kfA, 0); ATT_SB;
;                         ATT_VISSUE(vAl, vAh, 0); ATT_SMMA(s1, kfB, NC - 1); ATT_SOFT(s0, 0); ATT_SB;
;                         ATT_SOFT(s1, NC - 1); ATT_PVW(0, vAl, vAh, 0); ATT_SB;
;                         ATT_VISSUE(vBl, vBh, 4); ATT_PV(NC - 1, vAl, vAh, 0); ATT_SB;
;                         ATT_PVW(0, vBl, vBh, 4); ATT_PV(NC - 1, vBl, vBh, 4); ATT_SB; }
;     ...
;         if (kt + 1 < nkt) { if (more2) ATT_WAITBAR_ONE(); else ATT_WAITBAR_ALL(); }
.Ldx_nd:
	s_waitcnt lgkmcnt(15)
	v_mfma_f32_16x16x32_bf16 v[188:191], v[84:87], v[80:83], v[0:3]
	v_mfma_f32_16x16x32_bf16 v[192:195], v[88:91], v[80:83], v[0:3]
	v_mfma_f32_16x16x32_bf16 v[196:199], v[100:103], v[80:83], v[0:3]
	v_mfma_f32_16x16x32_bf16 v[200:203], v[104:107], v[80:83], v[0:3]
	v_mfma_f32_16x16x32_bf16 v[188:191], v[92:95], v[76:79], v[188:191]
	v_mfma_f32_16x16x32_bf16 v[192:195], v[96:99], v[76:79], v[192:195]
	v_mfma_f32_16x16x32_bf16 v[196:199], v[108:111], v[76:79], v[196:199]
	v_mfma_f32_16x16x32_bf16 v[200:203], v[112:115], v[76:79], v[200:203]
	ds_read_b128 v[84:87], v116 offset:8192
	ds_read_b128 v[88:91], v116 offset:10240
	ds_read_b128 v[92:95], v117 offset:8192
	ds_read_b128 v[96:99], v117 offset:10240
	ds_read_b128 v[100:103], v116 offset:12288
	ds_read_b128 v[104:107], v116 offset:14336
	ds_read_b128 v[108:111], v117 offset:12288
	ds_read_b128 v[112:115], v117 offset:14336
	s_cmp_lt_u32 s15, s70
	s_cbranch_scc1 .Ldx_sw4
	s_waitcnt vmcnt(0)
	s_branch .Ldx_sb
.Ldx_sw4:
	s_waitcnt vmcnt(4)
.Ldx_sb:
	s_barrier
	s_waitcnt lgkmcnt(15)
	v_mfma_f32_16x16x32_bf16 v[32:35], v[148:151], v[220:223], v[32:35]
	v_exp_f32_e32 v188, v188
	v_mfma_f32_16x16x32_bf16 v[24:27], v[156:159], v[220:223], v[24:27]
	v_exp_f32_e32 v189, v189
	v_mfma_f32_16x16x32_bf16 v[28:31], v[148:151], v[228:231], v[28:31]
	v_exp_f32_e32 v190, v190
	v_mfma_f32_16x16x32_bf16 v[20:23], v[156:159], v[228:231], v[20:23]
	v_exp_f32_e32 v191, v191
	v_mfma_f32_16x16x32_bf16 v[32:35], v[152:155], v[224:227], v[32:35]
	v_exp_f32_e32 v192, v192
	v_mfma_f32_16x16x32_bf16 v[24:27], v[160:163], v[224:227], v[24:27]
	v_exp_f32_e32 v193, v193
	v_mfma_f32_16x16x32_bf16 v[28:31], v[152:155], v[232:235], v[28:31]
	v_exp_f32_e32 v194, v194
	v_mfma_f32_16x16x32_bf16 v[20:23], v[160:163], v[232:235], v[20:23]
	v_exp_f32_e32 v195, v195
	s_waitcnt lgkmcnt(8)
	v_mfma_f32_16x16x32_bf16 v[16:19], v[164:167], v[220:223], v[16:19]
	v_exp_f32_e32 v196, v196
	v_mfma_f32_16x16x32_bf16 v[8:11], v[172:175], v[220:223], v[8:11]
	v_exp_f32_e32 v197, v197
	v_mfma_f32_16x16x32_bf16 v[12:15], v[164:167], v[228:231], v[12:15]
	v_exp_f32_e32 v198, v198
	v_mfma_f32_16x16x32_bf16 v[4:7], v[172:175], v[228:231], v[4:7]
	v_exp_f32_e32 v199, v199
	v_mfma_f32_16x16x32_bf16 v[16:19], v[168:171], v[224:227], v[16:19]
	v_exp_f32_e32 v200, v200
	v_mfma_f32_16x16x32_bf16 v[8:11], v[176:179], v[224:227], v[8:11]
	v_exp_f32_e32 v201, v201
	v_mfma_f32_16x16x32_bf16 v[12:15], v[168:171], v[232:235], v[12:15]
	v_exp_f32_e32 v202, v202
	v_mfma_f32_16x16x32_bf16 v[4:7], v[176:179], v[232:235], v[4:7]
	v_exp_f32_e32 v203, v203
	s_waitcnt lgkmcnt(0)
	v_mfma_f32_16x16x32_bf16 v[204:207], v[84:87], v[72:75], v[0:3]
	v_mfma_f32_16x16x32_bf16 v[208:211], v[88:91], v[72:75], v[0:3]
	v_mfma_f32_16x16x32_bf16 v[212:215], v[100:103], v[72:75], v[0:3]
	v_mfma_f32_16x16x32_bf16 v[216:219], v[104:107], v[72:75], v[0:3]
	v_mfma_f32_16x16x32_bf16 v[204:207], v[92:95], v[68:71], v[204:207]
	v_cvt_pk_bf16_f32 v220, v188, v189
	v_cvt_pk_bf16_f32 v221, v190, v191
	v_mfma_f32_16x16x32_bf16 v[208:211], v[96:99], v[68:71], v[208:211]
	v_cvt_pk_bf16_f32 v222, v192, v193
	v_cvt_pk_bf16_f32 v223, v194, v195
	v_mfma_f32_16x16x32_bf16 v[212:215], v[108:111], v[68:71], v[212:215]
	v_cvt_pk_bf16_f32 v224, v196, v197
	v_cvt_pk_bf16_f32 v225, v198, v199
	v_mfma_f32_16x16x32_bf16 v[216:219], v[112:115], v[68:71], v[216:219]
	v_cvt_pk_bf16_f32 v226, v200, v201
	v_cvt_pk_bf16_f32 v227, v202, v203
	v_add_u32_e32 v118, s0, v143
	v_add_u32_e32 v120, v118, v142
	v_add_u32_e32 v121, v118, v141
	v_add_u32_e32 v122, v118, v140
	v_add_u32_e32 v123, v118, v139
	ds_read_b64_tr_b16 v[148:149], v120
	ds_read_b64_tr_b16 v[150:151], v120 offset:4096
	ds_read_b64_tr_b16 v[152:153], v120 offset:8192
	ds_read_b64_tr_b16 v[154:155], v120 offset:12288
	ds_read_b64_tr_b16 v[156:157], v121
	ds_read_b64_tr_b16 v[158:159], v121 offset:4096
	ds_read_b64_tr_b16 v[160:161], v121 offset:8192
	ds_read_b64_tr_b16 v[162:163], v121 offset:12288
	ds_read_b64_tr_b16 v[164:165], v122
	ds_read_b64_tr_b16 v[166:167], v122 offset:4096
	ds_read_b64_tr_b16 v[168:169], v122 offset:8192
	ds_read_b64_tr_b16 v[170:171], v122 offset:12288
	ds_read_b64_tr_b16 v[172:173], v123
	ds_read_b64_tr_b16 v[174:175], v123 offset:4096
	ds_read_b64_tr_b16 v[176:177], v123 offset:8192
	ds_read_b64_tr_b16 v[178:179], v123 offset:12288
	v_exp_f32_e32 v204, v204
	v_exp_f32_e32 v205, v205
	v_exp_f32_e32 v206, v206
	v_exp_f32_e32 v207, v207
	v_exp_f32_e32 v208, v208
	v_exp_f32_e32 v209, v209
	v_exp_f32_e32 v210, v210
	v_exp_f32_e32 v211, v211
	v_exp_f32_e32 v212, v212
	v_exp_f32_e32 v213, v213
	v_exp_f32_e32 v214, v214
	v_exp_f32_e32 v215, v215
	v_exp_f32_e32 v216, v216
	v_exp_f32_e32 v217, v217
	v_exp_f32_e32 v218, v218
	v_exp_f32_e32 v219, v219
	v_cvt_pk_bf16_f32 v228, v204, v205
	v_cvt_pk_bf16_f32 v229, v206, v207
	v_cvt_pk_bf16_f32 v230, v208, v209
	v_cvt_pk_bf16_f32 v231, v210, v211
	v_cvt_pk_bf16_f32 v232, v212, v213
	v_cvt_pk_bf16_f32 v233, v214, v215
	v_cvt_pk_bf16_f32 v234, v216, v217
	v_cvt_pk_bf16_f32 v235, v218, v219
	s_branch .Ldx_end
; #define ATT_WAITBAR_ALL() asm volatile("s_waitcnt vmcnt(0) lgkmcnt(0)\n\ts_barrier" ::: "memory")
; #define ATT_WAITBAR_ONE() do { if (DIFF) asm volatile("s_waitcnt vmcnt(4) lgkmcnt(0)\n\ts_barrier" ::: "memory"); else asm volatile("s_waitcnt vmcnt(3) lgkmcnt(0)\n\ts_barrier" ::: "memory"); } while (0)
; #define ATT_KREAD(dst, c) do { _Pragma("unroll") for (int kb = 0; kb < 4; ++kb) _Pragma("unroll") for (int ds = 0; ds < 2; ++ds) \
;                 dst[kb * 2 + ds] = *(const LAS bf16x8*)(bp + (c) * 8192 + kb * 2048 + kfo + (((unsigned)(4 * ds + quad) ^ ksw) * 16)); } while (0)
; #define ATT_SMMA(sv, kf, c) do { _Pragma("unroll") for (int kb = 0; kb < 4; ++kb) { sv[kb] = (f32x4){sinit, sinit, sinit, sinit}; _Pragma("unroll") for (int ds = 0; ds < 2; ++ds) \
;                 sv[kb] = __builtin_amdgcn_mfma_f32_16x16x32_bf16(kf[kb * 2 + ds], qf[c][ds], sv[kb], 0, 0, 0); } } while (0)
; #define ATT_PV(c, lo_, hi_, eb0) do { _Pragma("unroll") for (int e = 0; e < 4; ++e) _Pragma("unroll") for (int ks = 0; ks < 2; ++ks) \
;                 O[c][(eb0) + e] = __builtin_amdgcn_mfma_f32_16x16x32_bf16(__builtin_shufflevector(lo_[e * 2 + ks], hi_[e * 2 + ks], 0, 1, 2, 3, 4, 5, 6, 7), P[c][ks], O[c][(eb0) + e], 0, 0, 0); } while (0)
; #define ATT_PVW(c, lo_, hi_, eb0) do { ATT_W4(12, lo_, hi_, 0); ATT_PV1(c, lo_, hi_, eb0, 0); ATT_W4(8, lo_, hi_, 1); ATT_PV1(c, lo_, hi_, eb0, 1); \
;                 ATT_W4(4, lo_, hi_, 2); ATT_PV1(c, lo_, hi_, eb0, 2); ATT_W4(0, lo_, hi_, 3); ATT_PV1(c, lo_, hi_, eb0, 3); } while (0)
; #define ATT_SB __builtin_amdgcn_sched_barrier(0)
; template <bool DIFF>
; __device__ __forceinline__ void attn_item(LAS unsigned char* lds, const bf16_t* Z, bf16_t* MIX, int b, int h, int t, float lam, float shift, const float* gain, int tid, int wid, int lane) {
;     ...
;             ATT_KREAD(kfA, 0); ATT_SB;
;             if (DIFF) { ATT_KREAD(kfB, NC - 1); ATT_SMMA(s0, kfA, 0); ATT_SB;
;                         ATT_VISSUE(vAl, vAh, 0); ATT_SMMA(s1, kfB, NC - 1); ATT_SOFT(s0, 0); ATT_SB;
;                         ATT_SOFT(s1, NC - 1); ATT_PVW(0, vAl, vAh, 0); ATT_SB;
;                         ATT_VISSUE(vBl, vBh, 4); ATT_PV(NC - 1, vAl, vAh, 0); ATT_SB;
;                         ATT_PVW(0, vBl, vBh, 4); ATT_PV(NC - 1, vBl, vBh, 4); ATT_SB; }
;     ...
;         if (kt + 1 < nkt) { if (more2) ATT_WAITBAR_ONE(); else ATT_WAITBAR_ALL(); }
.Ldx_pvo:
	s_waitcnt lgkmcnt(0)
	v_add_u32_e32 v118, s1, v143
	v_add_u32_e32 v120, v118, v138
	v_add_u32_e32 v121, v118, v137
	v_add_u32_e32 v122, v118, v136
	v_add_u32_e32 v123, v118, v129
	v_mfma_f32_16x16x32_bf16 v[64:67], v[148:151], v[220:223], v[64:67]
	v_add_f32_e32 v131, v131, v188
	v_add_f32_e32 v131, v131, v189
	v_mfma_f32_16x16x32_bf16 v[60:63], v[156:159], v[220:223], v[60:63]
	v_add_f32_e32 v131, v131, v190
	v_add_f32_e32 v131, v131, v191
	v_mfma_f32_16x16x32_bf16 v[56:59], v[148:151], v[228:231], v[56:59]
	v_add_f32_e32 v131, v131, v192
	v_add_f32_e32 v131, v131, v193
	v_mfma_f32_16x16x32_bf16 v[52:55], v[156:159], v[228:231], v[52:55]
	v_add_f32_e32 v131, v131, v194
	v_add_f32_e32 v131, v131, v195
	v_mfma_f32_16x16x32_bf16 v[64:67], v[152:155], v[224:227], v[64:67]
	v_add_f32_e32 v131, v131, v196
	v_add_f32_e32 v131, v131, v197
	v_mfma_f32_16x16x32_bf16 v[60:63], v[160:163], v[224:227], v[60:63]
	v_add_f32_e32 v131, v131, v198
	v_add_f32_e32 v131, v131, v199
	v_mfma_f32_16x16x32_bf16 v[56:59], v[152:155], v[232:235], v[56:59]
	v_add_f32_e32 v131, v131, v200
	v_add_f32_e32 v131, v131, v201
	v_mfma_f32_16x16x32_bf16 v[52:55], v[160:163], v[232:235], v[52:55]
	v_add_f32_e32 v131, v131, v202
	v_add_f32_e32 v131, v131, v203
	ds_read_b64_tr_b16 v[148:149], v120
	ds_read_b64_tr_b16 v[150:151], v120 offset:4096
	ds_read_b64_tr_b16 v[152:153], v120 offset:8192
	ds_read_b64_tr_b16 v[154:155], v120 offset:12288
	ds_read_b64_tr_b16 v[156:157], v121
	ds_read_b64_tr_b16 v[158:159], v121 offset:4096
	ds_read_b64_tr_b16 v[160:161], v121 offset:8192
	ds_read_b64_tr_b16 v[162:163], v121 offset:12288
	v_mfma_f32_16x16x32_bf16 v[48:51], v[164:167], v[220:223], v[48:51]
	v_add_f32_e32 v130, v130, v204
	v_add_f32_e32 v130, v130, v205
	v_mfma_f32_16x16x32_bf16 v[40:43], v[172:175], v[220:223], v[40:43]
	v_add_f32_e32 v130, v130, v206
	v_add_f32_e32 v130, v130, v207
	v_mfma_f32_16x16x32_bf16 v[44:47], v[164:167], v[228:231], v[44:47]
	v_add_f32_e32 v130, v130, v208
	v_add_f32_e32 v130, v130, v209
	v_mfma_f32_16x16x32_bf16 v[36:39], v[172:175], v[228:231], v[36:39]
	v_add_f32_e32 v130, v130, v210
	v_add_f32_e32 v130, v130, v211
	v_mfma_f32_16x16x32_bf16 v[48:51], v[168:171], v[224:227], v[48:51]
	v_add_f32_e32 v130, v130, v212
	v_add_f32_e32 v130, v130, v213
	v_mfma_f32_16x16x32_bf16 v[40:43], v[176:179], v[224:227], v[40:43]
	v_add_f32_e32 v130, v130, v214
	v_add_f32_e32 v130, v130, v215
	v_mfma_f32_16x16x32_bf16 v[44:47], v[168:171], v[232:235], v[44:47]
	v_add_f32_e32 v130, v130, v216
	v_add_f32_e32 v130, v130, v217
	v_mfma_f32_16x16x32_bf16 v[36:39], v[176:179], v[232:235], v[36:39]
	v_add_f32_e32 v130, v130, v218
	v_add_f32_e32 v130, v130, v219
	ds_read_b64_tr_b16 v[164:165], v122
	ds_read_b64_tr_b16 v[166:167], v122 offset:4096
	ds_read_b64_tr_b16 v[168:169], v122 offset:8192
	ds_read_b64_tr_b16 v[170:171], v122 offset:12288
	ds_read_b64_tr_b16 v[172:173], v123
	ds_read_b64_tr_b16 v[174:175], v123 offset:4096
	ds_read_b64_tr_b16 v[176:177], v123 offset:8192
	ds_read_b64_tr_b16 v[178:179], v123 offset:12288
	s_cmp_lt_u32 s15, s70
	s_cbranch_scc1 .Ldx_pw4
	s_waitcnt vmcnt(0)
	s_branch .Ldx_pb

; #define ATT_WAITBAR_ALL() asm volatile("s_waitcnt vmcnt(0) lgkmcnt(0)\n\ts_barrier" ::: "memory")
; #define ATT_WAITBAR_ONE() do { if (DIFF) asm volatile("s_waitcnt vmcnt(4) lgkmcnt(0)\n\ts_barrier" ::: "memory"); else asm volatile("s_waitcnt vmcnt(3) lgkmcnt(0)\n\ts_barrier" ::: "memory"); } while (0)
; #define ATT_KREAD(dst, c) do { _Pragma("unroll") for (int kb = 0; kb < 4; ++kb) _Pragma("unroll") for (int ds = 0; ds < 2; ++ds) \
;                 dst[kb * 2 + ds] = *(const LAS bf16x8*)(bp + (c) * 8192 + kb * 2048 + kfo + (((unsigned)(4 * ds + quad) ^ ksw) * 16)); } while (0)
; #define ATT_SMMA(sv, kf, c) do { _Pragma("unroll") for (int kb = 0; kb < 4; ++kb) { sv[kb] = (f32x4){sinit, sinit, sinit, sinit}; _Pragma("unroll") for (int ds = 0; ds < 2; ++ds) \
;                 sv[kb] = __builtin_amdgcn_mfma_f32_16x16x32_bf16(kf[kb * 2 + ds], qf[c][ds], sv[kb], 0, 0, 0); } } while (0)
; #define ATT_PV(c, lo_, hi_, eb0) do { _Pragma("unroll") for (int e = 0; e < 4; ++e) _Pragma("unroll") for (int ks = 0; ks < 2; ++ks) \
;                 O[c][(eb0) + e] = __builtin_amdgcn_mfma_f32_16x16x32_bf16(__builtin_shufflevector(lo_[e * 2 + ks], hi_[e * 2 + ks], 0, 1, 2, 3, 4, 5, 6, 7), P[c][ks], O[c][(eb0) + e], 0, 0, 0); } while (0)
; #define ATT_PVW(c, lo_, hi_, eb0) do { ATT_W4(12, lo_, hi_, 0); ATT_PV1(c, lo_, hi_, eb0, 0); ATT_W4(8, lo_, hi_, 1); ATT_PV1(c, lo_, hi_, eb0, 1); \
;                 ATT_W4(4, lo_, hi_, 2); ATT_PV1(c, lo_, hi_, eb0, 2); ATT_W4(0, lo_, hi_, 3); ATT_PV1(c, lo_, hi_, eb0, 3); } while (0)
; #define ATT_SB __builtin_amdgcn_sched_barrier(0)
; template <bool DIFF>
; __device__ __forceinline__ void attn_item(LAS unsigned char* lds, const bf16_t* Z, bf16_t* MIX, int b, int h, int t, float lam, float shift, const float* gain, int tid, int wid, int lane) {
;     ...
;             ATT_KREAD(kfA, 0); ATT_SB;
;             if (DIFF) { ATT_KREAD(kfB, NC - 1); ATT_SMMA(s0, kfA, 0); ATT_SB;
;                         ATT_VISSUE(vAl, vAh, 0); ATT_SMMA(s1, kfB, NC - 1); ATT_SOFT(s0, 0); ATT_SB;
;                         ATT_SOFT(s1, NC - 1); ATT_PVW(0, vAl, vAh, 0); ATT_SB;
;                         ATT_VISSUE(vBl, vBh, 4); ATT_PV(NC - 1, vAl, vAh, 0); ATT_SB;
;                         ATT_PVW(0, vBl, vBh, 4); ATT_PV(NC - 1, vBl, vBh, 4); ATT_SB; }
;     ...
;         if (kt + 1 < nkt) { if (more2) ATT_WAITBAR_ONE(); else ATT_WAITBAR_ALL(); }
.Ldx_pb:
	s_barrier
	s_waitcnt lgkmcnt(8)
	v_mfma_f32_16x16x32_bf16 v[32:35], v[148:151], v[220:223], v[32:35]
	v_mfma_f32_16x16x32_bf16 v[24:27], v[156:159], v[220:223], v[24:27]
	v_mfma_f32_16x16x32_bf16 v[28:31], v[148:151], v[228:231], v[28:31]
	v_mfma_f32_16x16x32_bf16 v[20:23], v[156:159], v[228:231], v[20:23]
	v_mfma_f32_16x16x32_bf16 v[32:35], v[152:155], v[224:227], v[32:35]
	v_mfma_f32_16x16x32_bf16 v[24:27], v[160:163], v[224:227], v[24:27]
	v_mfma_f32_16x16x32_bf16 v[28:31], v[152:155], v[232:235], v[28:31]
	v_mfma_f32_16x16x32_bf16 v[20:23], v[160:163], v[232:235], v[20:23]
	s_waitcnt lgkmcnt(0)
	v_mfma_f32_16x16x32_bf16 v[16:19], v[164:167], v[220:223], v[16:19]
	v_mfma_f32_16x16x32_bf16 v[8:11], v[172:175], v[220:223], v[8:11]
	v_mfma_f32_16x16x32_bf16 v[12:15], v[164:167], v[228:231], v[12:15]
	v_mfma_f32_16x16x32_bf16 v[4:7], v[172:175], v[228:231], v[4:7]
	v_mfma_f32_16x16x32_bf16 v[16:19], v[168:171], v[224:227], v[16:19]
	v_mfma_f32_16x16x32_bf16 v[8:11], v[176:179], v[224:227], v[8:11]
	v_mfma_f32_16x16x32_bf16 v[12:15], v[168:171], v[232:235], v[12:15]
	v_mfma_f32_16x16x32_bf16 v[4:7], v[176:179], v[232:235], v[4:7]
.Ldx_end:
	s_add_i32 s15, s15, 1
	s_add_i32 s2, s70, 2
	s_cmp_ge_u32 s15, s2
	s_cbranch_scc1 .Ldx_exit
	s_barrier
	s_branch .Ldx_loop
.Ldx_exit:
	s_add_i32 s2, s70, 1
	s_cmp_le_u32 s2, s83
	s_cbranch_scc0 .Ldx_xb
	s_and_b32 s1, s2, 3
	s_lshl_b32 s1, s1, 15
	s_waitcnt lgkmcnt(0)
	v_add_u32_e32 v118, s1, v143
	v_add_u32_e32 v120, v118, v138
	v_add_u32_e32 v121, v118, v137
	v_add_u32_e32 v122, v118, v136
	v_add_u32_e32 v123, v118, v129
	v_mfma_f32_16x16x32_bf16 v[64:67], v[148:151], v[220:223], v[64:67]
	v_add_f32_e32 v131, v131, v188
	v_add_f32_e32 v131, v131, v189
	v_mfma_f32_16x16x32_bf16 v[60:63], v[156:159], v[220:223], v[60:63]
	v_add_f32_e32 v131, v131, v190
	v_add_f32_e32 v131, v131, v191
	v_mfma_f32_16x16x32_bf16 v[56:59], v[148:151], v[228:231], v[56:59]
	v_add_f32_e32 v131, v131, v192
	v_add_f32_e32 v131, v131, v193
	v_mfma_f32_16x16x32_bf16 v[52:55], v[156:159], v[228:231], v[52:55]
	v_add_f32_e32 v131, v131, v194
	v_add_f32_e32 v131, v131, v195
	v_mfma_f32_16x16x32_bf16 v[64:67], v[152:155], v[224:227], v[64:67]
	v_add_f32_e32 v131, v131, v196
	v_add_f32_e32 v131, v131, v197
	v_mfma_f32_16x16x32_bf16 v[60:63], v[160:163], v[224:227], v[60:63]
	v_add_f32_e32 v131, v131, v198
	v_add_f32_e32 v131, v131, v199
	v_mfma_f32_16x16x32_bf16 v[56:59], v[152:155], v[232:235], v[56:59]
	v_add_f32_e32 v131, v131, v200
	v_add_f32_e32 v131, v131, v201
	v_mfma_f32_16x16x32_bf16 v[52:55], v[160:163], v[232:235], v[52:55]
	v_add_f32_e32 v131, v131, v202
	v_add_f32_e32 v131, v131, v203
	ds_read_b64_tr_b16 v[148:149], v120
	ds_read_b64_tr_b16 v[150:151], v120 offset:4096
	ds_read_b64_tr_b16 v[152:153], v120 offset:8192
	ds_read_b64_tr_b16 v[154:155], v120 offset:12288
	ds_read_b64_tr_b16 v[156:157], v121
	ds_read_b64_tr_b16 v[158:159], v121 offset:4096
	ds_read_b64_tr_b16 v[160:161], v121 offset:8192
	ds_read_b64_tr_b16 v[162:163], v121 offset:12288
	v_mfma_f32_16x16x32_bf16 v[48:51], v[164:167], v[220:223], v[48:51]
	v_add_f32_e32 v130, v130, v204
	v_add_f32_e32 v130, v130, v205
	v_mfma_f32_16x16x32_bf16 v[40:43], v[172:175], v[220:223], v[40:43]
	v_add_f32_e32 v130, v130, v206
	v_add_f32_e32 v130, v130, v207
	v_mfma_f32_16x16x32_bf16 v[44:47], v[164:167], v[228:231], v[44:47]
	v_add_f32_e32 v130, v130, v208
	v_add_f32_e32 v130, v130, v209
	v_mfma_f32_16x16x32_bf16 v[36:39], v[172:175], v[228:231], v[36:39]
	v_add_f32_e32 v130, v130, v210
	v_add_f32_e32 v130, v130, v211
	v_mfma_f32_16x16x32_bf16 v[48:51], v[168:171], v[224:227], v[48:51]
	v_add_f32_e32 v130, v130, v212
	v_add_f32_e32 v130, v130, v213
	v_mfma_f32_16x16x32_bf16 v[40:43], v[176:179], v[224:227], v[40:43]
	v_add_f32_e32 v130, v130, v214
	v_add_f32_e32 v130, v130, v215
	v_mfma_f32_16x16x32_bf16 v[44:47], v[168:171], v[232:235], v[44:47]
	v_add_f32_e32 v130, v130, v216
	v_add_f32_e32 v130, v130, v217
	v_mfma_f32_16x16x32_bf16 v[36:39], v[176:179], v[232:235], v[36:39]
	v_add_f32_e32 v130, v130, v218
	v_add_f32_e32 v130, v130, v219
	ds_read_b64_tr_b16 v[164:165], v122
	ds_read_b64_tr_b16 v[166:167], v122 offset:4096
	ds_read_b64_tr_b16 v[168:169], v122 offset:8192
	ds_read_b64_tr_b16 v[170:171], v122 offset:12288
	ds_read_b64_tr_b16 v[172:173], v123
	ds_read_b64_tr_b16 v[174:175], v123 offset:4096
	ds_read_b64_tr_b16 v[176:177], v123 offset:8192
	ds_read_b64_tr_b16 v[178:179], v123 offset:12288
	s_waitcnt lgkmcnt(8)
	v_mfma_f32_16x16x32_bf16 v[32:35], v[148:151], v[220:223], v[32:35]
	v_mfma_f32_16x16x32_bf16 v[24:27], v[156:159], v[220:223], v[24:27]
	v_mfma_f32_16x16x32_bf16 v[28:31], v[148:151], v[228:231], v[28:31]
	v_mfma_f32_16x16x32_bf16 v[20:23], v[156:159], v[228:231], v[20:23]
	v_mfma_f32_16x16x32_bf16 v[32:35], v[152:155], v[224:227], v[32:35]
	v_mfma_f32_16x16x32_bf16 v[24:27], v[160:163], v[224:227], v[24:27]
	v_mfma_f32_16x16x32_bf16 v[28:31], v[152:155], v[232:235], v[28:31]
	v_mfma_f32_16x16x32_bf16 v[20:23], v[160:163], v[232:235], v[20:23]
	s_waitcnt lgkmcnt(0)
	v_mfma_f32_16x16x32_bf16 v[16:19], v[164:167], v[220:223], v[16:19]
	v_mfma_f32_16x16x32_bf16 v[8:11], v[172:175], v[220:223], v[8:11]
	v_mfma_f32_16x16x32_bf16 v[12:15], v[164:167], v[228:231], v[12:15]
	v_mfma_f32_16x16x32_bf16 v[4:7], v[172:175], v[228:231], v[4:7]
	v_mfma_f32_16x16x32_bf16 v[16:19], v[168:171], v[224:227], v[16:19]
	v_mfma_f32_16x16x32_bf16 v[8:11], v[176:179], v[224:227], v[8:11]
	v_mfma_f32_16x16x32_bf16 v[12:15], v[168:171], v[232:235], v[12:15]
	v_mfma_f32_16x16x32_bf16 v[4:7], v[176:179], v[232:235], v[4:7]
	s_branch .Ldx_done
.Ldx_xb:
	s_barrier
; __device__ __forceinline__ unsigned cvtpk(float lo, float hi) { f32x2 v = {lo, hi}; bf16x2_t b = __builtin_convertvector(v, bf16x2_t); return __builtin_bit_cast(unsigned, b); }
; __device__ __forceinline__ float bflo(unsigned u) { return __uint_as_float(u << 16); }
; __device__ __forceinline__ float bfhi(unsigned u) { return __uint_as_float(u & 0xffff0000u); }
; template <bool DIFF>
; __device__ __forceinline__ void attn_item(LAS unsigned char* lds, const bf16_t* Z, bf16_t* MIX, int b, int h, int t, float lam, float shift, const float* gain, int tid, int wid, int lane) {
;     ...
;     float inv0 = 1.f, inv1 = 0.f;
;     if (DIFF) {
; #pragma unroll
;         for (int c = 0; c < NC; ++c) l[c] = quad_sum(l[c]);
;         inv0 = 1.0f / l[0]; inv1 = lam / l[NC - 1];
;     }
;     float ss = 0.f;
; #pragma unroll
;     for (int eb = 0; eb < 8; ++eb)
; #pragma unroll
;         for (int i = 0; i < 4; ++i) { float v = O[0][eb][i] * inv0; if (DIFF) v -= O[NC - 1][eb][i] * inv1; O[0][eb][i] = v; ss += v * v; }
;     ss = quad_sum(ss);
;     const float r = rsqrtf(ss * (1.0f / 128.0f) + EPS) * (DIFF ? 0.8f : 1.0f);
;     const int row = row0 + q16;
;     const bf16_t* gp = Z + (size_t)row * DIN + gcol + 4 * quad;
;     bf16_t* op = MIX + (size_t)row * DM + (DIFF ? 1024 : 0) + 128 * h + 4 * quad;
; #pragma unroll
;     for (int eb = 0; eb < 8; ++eb) {
;         const u32x2 gw = *(const u32x2*)(gp + 16 * eb);
;         const f32x4 gn = *(const f32x4*)(gain + 16 * eb + 4 * quad);
;         u32x2 w; w.x = cvtpk(O[0][eb][0] * r * gn.x * bflo(gw.x), O[0][eb][1] * r * gn.y * bfhi(gw.x));
;         w.y = cvtpk(O[0][eb][2] * r * gn.z * bflo(gw.y), O[0][eb][3] * r * gn.w * bfhi(gw.y));
;         *(u32x2*)(op + 16 * eb) = w;
;     }
.Ldx_done:
.LBB0_574:
	s_waitcnt lgkmcnt(0)
	ds_swizzle_b32 v68, v131 offset:swizzle(SWAP,16)
	ds_swizzle_b32 v69, v130 offset:swizzle(SWAP,16)
	v_ashrrev_i32_e32 v129, 31, v128
	v_lshlrev_b64 v[80:81], 1, v[128:129]
	s_lshl_b32 s86, s80, 1
	s_waitcnt lgkmcnt(0)
	v_add_f32_e32 v68, v131, v68
	v_mov_b32_e32 v70, v68
	s_nop 1
	v_permlane32_swap_b32_e32 v68, v70
	v_add_f32_e32 v68, v68, v70
	v_div_scale_f32 v70, s[0:1], v68, v68, 1.0
	v_rcp_f32_e32 v72, v70
	v_add_f32_e32 v69, v130, v69
	v_mov_b32_e32 v71, v69
	s_nop 1
	v_permlane32_swap_b32_e32 v69, v71
	v_add_f32_e32 v69, v69, v71
	v_fma_f32 v71, -v70, v72, 1.0
	v_fmac_f32_e32 v72, v71, v72
	v_div_scale_f32 v71, vcc, 1.0, v68, 1.0
	v_mul_f32_e32 v73, v71, v72
	v_fma_f32 v74, -v70, v73, v71
	v_fmac_f32_e32 v73, v74, v72
	v_fma_f32 v70, -v70, v73, v71
	v_div_scale_f32 v71, s[0:1], v69, v69, s28
	v_rcp_f32_e32 v74, v71
	v_div_fmas_f32 v70, v70, v72, v73
	v_div_fixup_f32 v76, v70, v68, 1.0
	s_movk_i32 s0, 0x3000
	v_fma_f32 v68, -v71, v74, 1.0
	v_fmac_f32_e32 v74, v68, v74
	v_div_scale_f32 v68, vcc, s28, v69, s28
	v_mul_f32_e32 v70, v68, v74
	v_fma_f32 v72, -v71, v70, v68
	v_fmac_f32_e32 v70, v72, v74
	v_fma_f32 v68, -v71, v70, v68
	v_lshl_add_u64 v[72:73], v[126:127], 0, v[80:81]
	v_div_fmas_f32 v68, v68, v74, v70
	v_lshl_add_u64 v[70:71], v[72:73], 0, s[92:93]
	v_add_co_u32_e32 v72, vcc, s0, v72
	v_div_fixup_f32 v78, v68, v69, s28
	v_lshlrev_b64 v[68:69], 12, v[124:125]
	v_addc_co_u32_e32 v73, vcc, 0, v73, vcc
	v_lshl_add_u64 v[82:83], s[88:89], 0, v[68:69]
	v_lshl_add_u64 v[68:69], v[128:129], 2, s[84:85]
	global_load_dwordx2 v[116:117], v[70:71], off
	global_load_dwordx4 v[84:87], v[68:69], off
	global_load_dwordx2 v[118:119], v[70:71], off offset:32
	global_load_dwordx4 v[88:91], v[68:69], off offset:64
	global_load_dwordx2 v[120:121], v[70:71], off offset:64
	global_load_dwordx4 v[92:95], v[68:69], off offset:128
	global_load_dwordx2 v[122:123], v[70:71], off offset:96
	global_load_dwordx4 v[96:99], v[68:69], off offset:192
	global_load_dwordx2 v[132:133], v[70:71], off offset:128
	global_load_dwordx4 v[100:103], v[68:69], off offset:256
	global_load_dwordx2 v[134:135], v[70:71], off offset:160
	global_load_dwordx4 v[104:107], v[68:69], off offset:320
	global_load_dwordx2 v[136:137], v[70:71], off offset:192
	global_load_dwordx4 v[108:111], v[68:69], off offset:384
	global_load_dwordx2 v[138:139], v[70:71], off offset:224
	global_load_dwordx4 v[112:115], v[68:69], off offset:448
	v_pk_mul_f32 v[56:57], v[56:57], v[78:79] op_sel_hi:[1,0]
	v_pk_mul_f32 v[58:59], v[58:59], v[78:79] op_sel_hi:[1,0]
	v_pk_fma_f32 v[56:57], v[64:65], v[76:77], v[56:57] op_sel_hi:[1,0,1] neg_lo:[0,0,1] neg_hi:[0,0,1]
	v_pk_fma_f32 v[58:59], v[66:67], v[76:77], v[58:59] op_sel_hi:[1,0,1] neg_lo:[0,0,1] neg_hi:[0,0,1]
	v_pk_mul_f32 v[64:65], v[56:57], v[56:57]
	v_pk_mul_f32 v[66:67], v[58:59], v[58:59]
	v_pk_mul_f32 v[52:53], v[52:53], v[78:79] op_sel_hi:[1,0]
	v_add_f32_e32 v64, v64, v65
	v_pk_fma_f32 v[52:53], v[60:61], v[76:77], v[52:53] op_sel_hi:[1,0,1] neg_lo:[0,0,1] neg_hi:[0,0,1]
	v_add_f32_e32 v64, v66, v64
	v_pk_mul_f32 v[54:55], v[54:55], v[78:79] op_sel_hi:[1,0]
	v_pk_mul_f32 v[60:61], v[52:53], v[52:53]
	v_add_f32_e32 v64, v67, v64
	v_pk_fma_f32 v[54:55], v[62:63], v[76:77], v[54:55] op_sel_hi:[1,0,1] neg_lo:[0,0,1] neg_hi:[0,0,1]
	v_add_f32_e32 v60, v60, v64
	v_pk_mul_f32 v[62:63], v[54:55], v[54:55]
	v_pk_mul_f32 v[44:45], v[44:45], v[78:79] op_sel_hi:[1,0]
	v_add_f32_e32 v60, v61, v60
	v_pk_fma_f32 v[44:45], v[48:49], v[76:77], v[44:45] op_sel_hi:[1,0,1] neg_lo:[0,0,1] neg_hi:[0,0,1]
	v_add_f32_e32 v60, v62, v60
	v_pk_mul_f32 v[46:47], v[46:47], v[78:79] op_sel_hi:[1,0]
	v_pk_mul_f32 v[48:49], v[44:45], v[44:45]
	v_add_f32_e32 v60, v63, v60
	v_pk_fma_f32 v[46:47], v[50:51], v[76:77], v[46:47] op_sel_hi:[1,0,1] neg_lo:[0,0,1] neg_hi:[0,0,1]
	v_add_f32_e32 v48, v48, v60
	v_pk_mul_f32 v[50:51], v[46:47], v[46:47]
	v_pk_mul_f32 v[36:37], v[36:37], v[78:79] op_sel_hi:[1,0]
	v_add_f32_e32 v48, v49, v48
	v_pk_fma_f32 v[36:37], v[40:41], v[76:77], v[36:37] op_sel_hi:[1,0,1] neg_lo:[0,0,1] neg_hi:[0,0,1]
	v_add_f32_e32 v48, v50, v48
	v_pk_mul_f32 v[38:39], v[38:39], v[78:79] op_sel_hi:[1,0]
	v_pk_mul_f32 v[40:41], v[36:37], v[36:37]
	v_add_f32_e32 v48, v51, v48
	v_pk_fma_f32 v[38:39], v[42:43], v[76:77], v[38:39] op_sel_hi:[1,0,1] neg_lo:[0,0,1] neg_hi:[0,0,1]
	v_add_f32_e32 v40, v40, v48
	v_pk_mul_f32 v[42:43], v[38:39], v[38:39]
	v_pk_mul_f32 v[28:29], v[28:29], v[78:79] op_sel_hi:[1,0]
	v_add_f32_e32 v40, v41, v40
	v_pk_fma_f32 v[28:29], v[32:33], v[76:77], v[28:29] op_sel_hi:[1,0,1] neg_lo:[0,0,1] neg_hi:[0,0,1]
	v_add_f32_e32 v40, v42, v40
	v_pk_mul_f32 v[30:31], v[30:31], v[78:79] op_sel_hi:[1,0]
	v_pk_mul_f32 v[32:33], v[28:29], v[28:29]
	v_add_f32_e32 v40, v43, v40
	v_pk_fma_f32 v[30:31], v[34:35], v[76:77], v[30:31] op_sel_hi:[1,0,1] neg_lo:[0,0,1] neg_hi:[0,0,1]
	v_add_f32_e32 v32, v32, v40
	v_pk_mul_f32 v[34:35], v[30:31], v[30:31]
	v_pk_mul_f32 v[20:21], v[20:21], v[78:79] op_sel_hi:[1,0]
	v_add_f32_e32 v32, v33, v32
	v_pk_fma_f32 v[20:21], v[24:25], v[76:77], v[20:21] op_sel_hi:[1,0,1] neg_lo:[0,0,1] neg_hi:[0,0,1]
	v_add_f32_e32 v32, v34, v32
	v_pk_mul_f32 v[22:23], v[22:23], v[78:79] op_sel_hi:[1,0]
	v_pk_mul_f32 v[24:25], v[20:21], v[20:21]
	v_add_f32_e32 v32, v35, v32
	v_pk_fma_f32 v[22:23], v[26:27], v[76:77], v[22:23] op_sel_hi:[1,0,1] neg_lo:[0,0,1] neg_hi:[0,0,1]
	v_add_f32_e32 v24, v24, v32
	v_pk_mul_f32 v[26:27], v[22:23], v[22:23]
	v_pk_mul_f32 v[12:13], v[12:13], v[78:79] op_sel_hi:[1,0]
	v_add_f32_e32 v24, v25, v24
	v_pk_fma_f32 v[12:13], v[16:17], v[76:77], v[12:13] op_sel_hi:[1,0,1] neg_lo:[0,0,1] neg_hi:[0,0,1]
	v_add_f32_e32 v24, v26, v24
	v_pk_mul_f32 v[14:15], v[14:15], v[78:79] op_sel_hi:[1,0]
	v_pk_mul_f32 v[16:17], v[12:13], v[12:13]
	v_add_f32_e32 v24, v27, v24
	v_pk_fma_f32 v[14:15], v[18:19], v[76:77], v[14:15] op_sel_hi:[1,0,1] neg_lo:[0,0,1] neg_hi:[0,0,1]
	v_add_f32_e32 v16, v16, v24
	v_pk_mul_f32 v[18:19], v[14:15], v[14:15]
	v_pk_mul_f32 v[4:5], v[4:5], v[78:79] op_sel_hi:[1,0]
	v_add_f32_e32 v16, v17, v16
	v_pk_fma_f32 v[8:9], v[8:9], v[76:77], v[4:5] op_sel_hi:[1,0,1] neg_lo:[0,0,1] neg_hi:[0,0,1]
	v_add_f32_e32 v16, v18, v16
	v_pk_mul_f32 v[6:7], v[6:7], v[78:79] op_sel_hi:[1,0]
	v_pk_mul_f32 v[4:5], v[8:9], v[8:9]
	v_add_f32_e32 v16, v19, v16
	v_pk_fma_f32 v[10:11], v[10:11], v[76:77], v[6:7] op_sel_hi:[1,0,1] neg_lo:[0,0,1] neg_hi:[0,0,1]
	v_add_f32_e32 v4, v4, v16
	v_pk_mul_f32 v[6:7], v[10:11], v[10:11]
	v_add_f32_e32 v4, v5, v4
	v_add_f32_e32 v4, v6, v4
	v_add_f32_e32 v6, v7, v4
	ds_swizzle_b32 v7, v6 offset:swizzle(SWAP,16)
	v_mov_b32_e32 v18, 0x358637bd
	s_mov_b32 s87, s27
	v_lshl_add_u64 v[4:5], v[82:83], 0, s[86:87]
	v_lshl_add_u64 v[16:17], v[4:5], 0, v[80:81]
	s_waitcnt lgkmcnt(0)
; __device__ __forceinline__ unsigned cvtpk(float lo, float hi) { f32x2 v = {lo, hi}; bf16x2_t b = __builtin_convertvector(v, bf16x2_t); return __builtin_bit_cast(unsigned, b); }
; __device__ __forceinline__ float bflo(unsigned u) { return __uint_as_float(u << 16); }
; __device__ __forceinline__ float bfhi(unsigned u) { return __uint_as_float(u & 0xffff0000u); }
; template <bool DIFF>
; __device__ __forceinline__ void attn_item(LAS unsigned char* lds, const bf16_t* Z, bf16_t* MIX, int b, int h, int t, float lam, float shift, const float* gain, int tid, int wid, int lane) {
;     ...
;     ss = quad_sum(ss);
;     const float r = rsqrtf(ss * (1.0f / 128.0f) + EPS) * (DIFF ? 0.8f : 1.0f);
;     const int row = row0 + q16;
;     const bf16_t* gp = Z + (size_t)row * DIN + gcol + 4 * quad;
;     bf16_t* op = MIX + (size_t)row * DM + (DIFF ? 1024 : 0) + 128 * h + 4 * quad;
; #pragma unroll
;     for (int eb = 0; eb < 8; ++eb) {
;         const u32x2 gw = *(const u32x2*)(gp + 16 * eb);
;         const f32x4 gn = *(const f32x4*)(gain + 16 * eb + 4 * quad);
;         u32x2 w; w.x = cvtpk(O[0][eb][0] * r * gn.x * bflo(gw.x), O[0][eb][1] * r * gn.y * bfhi(gw.x));
;         w.y = cvtpk(O[0][eb][2] * r * gn.z * bflo(gw.y), O[0][eb][3] * r * gn.w * bfhi(gw.y));
;         *(u32x2*)(op + 16 * eb) = w;
	v_add_f32_e32 v6, v6, v7
	v_mov_b32_e32 v7, v6
	s_nop 1
	v_permlane32_swap_b32_e32 v6, v7
	v_add_f32_e32 v6, v6, v7
	v_fmamk_f32 v6, v6, 0x3c000000, v18
	v_mul_f32_e32 v7, 0x4b800000, v6
	v_cmp_gt_f32_e32 vcc, s42, v6
	s_nop 1
	v_cndmask_b32_e32 v6, v6, v7, vcc
	v_rsq_f32_e32 v24, v6
	s_nop 0
	v_mul_f32_e32 v25, 0x45800000, v24
	v_cndmask_b32_e32 v24, v24, v25, vcc
	v_mul_f32_e32 v24, 0x3f4ccccd, v24
	s_waitcnt vmcnt(0)
	v_pk_mul_f32 v[56:57], v[56:57], v[24:25] op_sel_hi:[1,0]
	v_pk_mul_f32 v[58:59], v[58:59], v[24:25] op_sel_hi:[1,0]
	v_lshlrev_b32_e32 v60, 16, v116
	v_and_b32_e32 v61, 0xffff0000, v116
	v_lshlrev_b32_e32 v62, 16, v117
	v_and_b32_e32 v63, 0xffff0000, v117
	v_pk_mul_f32 v[56:57], v[84:85], v[56:57]
	v_pk_mul_f32 v[58:59], v[86:87], v[58:59]
	v_pk_mul_f32 v[56:57], v[56:57], v[60:61]
	v_pk_mul_f32 v[58:59], v[58:59], v[62:63]
	v_cvt_pk_bf16_f32 v56, v56, v57
	v_cvt_pk_bf16_f32 v57, v58, v59
	global_store_dwordx2 v[16:17], v[56:57], off offset:2048
	v_pk_mul_f32 v[52:53], v[52:53], v[24:25] op_sel_hi:[1,0]
	v_pk_mul_f32 v[54:55], v[54:55], v[24:25] op_sel_hi:[1,0]
	v_lshlrev_b32_e32 v40, 16, v118
	v_and_b32_e32 v41, 0xffff0000, v118
	v_lshlrev_b32_e32 v42, 16, v119
	v_and_b32_e32 v43, 0xffff0000, v119
	v_pk_mul_f32 v[52:53], v[88:89], v[52:53]
	v_pk_mul_f32 v[54:55], v[90:91], v[54:55]
	v_pk_mul_f32 v[52:53], v[52:53], v[40:41]
	v_pk_mul_f32 v[54:55], v[54:55], v[42:43]
	v_cvt_pk_bf16_f32 v52, v52, v53
	v_cvt_pk_bf16_f32 v53, v54, v55
	global_store_dwordx2 v[16:17], v[52:53], off offset:2080
	v_pk_mul_f32 v[44:45], v[44:45], v[24:25] op_sel_hi:[1,0]
	v_pk_mul_f32 v[46:47], v[46:47], v[24:25] op_sel_hi:[1,0]
	v_lshlrev_b32_e32 v60, 16, v120
	v_and_b32_e32 v61, 0xffff0000, v120
	v_lshlrev_b32_e32 v62, 16, v121
	v_and_b32_e32 v63, 0xffff0000, v121
	v_pk_mul_f32 v[44:45], v[92:93], v[44:45]
	v_pk_mul_f32 v[46:47], v[94:95], v[46:47]
	v_pk_mul_f32 v[44:45], v[44:45], v[60:61]
	v_pk_mul_f32 v[46:47], v[46:47], v[62:63]
	v_cvt_pk_bf16_f32 v44, v44, v45
	v_cvt_pk_bf16_f32 v45, v46, v47
	global_store_dwordx2 v[16:17], v[44:45], off offset:2112
	v_pk_mul_f32 v[36:37], v[36:37], v[24:25] op_sel_hi:[1,0]
	v_pk_mul_f32 v[38:39], v[38:39], v[24:25] op_sel_hi:[1,0]
	v_lshlrev_b32_e32 v40, 16, v122
	v_and_b32_e32 v41, 0xffff0000, v122
	v_lshlrev_b32_e32 v42, 16, v123
	v_and_b32_e32 v43, 0xffff0000, v123
	v_pk_mul_f32 v[36:37], v[96:97], v[36:37]
	v_pk_mul_f32 v[38:39], v[98:99], v[38:39]
	v_pk_mul_f32 v[36:37], v[36:37], v[40:41]
	v_pk_mul_f32 v[38:39], v[38:39], v[42:43]
	v_cvt_pk_bf16_f32 v36, v36, v37
	v_cvt_pk_bf16_f32 v37, v38, v39
	global_store_dwordx2 v[16:17], v[36:37], off offset:2144
	v_pk_mul_f32 v[28:29], v[28:29], v[24:25] op_sel_hi:[1,0]
	v_pk_mul_f32 v[30:31], v[30:31], v[24:25] op_sel_hi:[1,0]
	v_lshlrev_b32_e32 v60, 16, v132
	v_and_b32_e32 v61, 0xffff0000, v132
	v_lshlrev_b32_e32 v62, 16, v133
	v_and_b32_e32 v63, 0xffff0000, v133
	v_pk_mul_f32 v[28:29], v[100:101], v[28:29]
	v_pk_mul_f32 v[30:31], v[102:103], v[30:31]
	v_pk_mul_f32 v[28:29], v[28:29], v[60:61]
	v_pk_mul_f32 v[30:31], v[30:31], v[62:63]
	v_cvt_pk_bf16_f32 v28, v28, v29
	v_cvt_pk_bf16_f32 v29, v30, v31
	global_store_dwordx2 v[16:17], v[28:29], off offset:2176
	v_pk_mul_f32 v[20:21], v[20:21], v[24:25] op_sel_hi:[1,0]
	v_pk_mul_f32 v[22:23], v[22:23], v[24:25] op_sel_hi:[1,0]
	v_lshlrev_b32_e32 v40, 16, v134
	v_and_b32_e32 v41, 0xffff0000, v134
	v_lshlrev_b32_e32 v42, 16, v135
	v_and_b32_e32 v43, 0xffff0000, v135
	v_pk_mul_f32 v[20:21], v[104:105], v[20:21]
	v_pk_mul_f32 v[22:23], v[106:107], v[22:23]
	v_pk_mul_f32 v[20:21], v[20:21], v[40:41]
	v_pk_mul_f32 v[22:23], v[22:23], v[42:43]
	v_cvt_pk_bf16_f32 v20, v20, v21
	v_cvt_pk_bf16_f32 v21, v22, v23
	global_store_dwordx2 v[16:17], v[20:21], off offset:2208
	v_pk_mul_f32 v[12:13], v[12:13], v[24:25] op_sel_hi:[1,0]
	v_pk_mul_f32 v[14:15], v[14:15], v[24:25] op_sel_hi:[1,0]
	v_lshlrev_b32_e32 v60, 16, v136
	v_and_b32_e32 v61, 0xffff0000, v136
	v_lshlrev_b32_e32 v62, 16, v137
	v_and_b32_e32 v63, 0xffff0000, v137
	v_pk_mul_f32 v[12:13], v[108:109], v[12:13]
	v_pk_mul_f32 v[14:15], v[110:111], v[14:15]
	v_pk_mul_f32 v[12:13], v[12:13], v[60:61]
	v_pk_mul_f32 v[14:15], v[14:15], v[62:63]
	v_cvt_pk_bf16_f32 v12, v12, v13
	v_cvt_pk_bf16_f32 v13, v14, v15
	global_store_dwordx2 v[16:17], v[12:13], off offset:2240
	v_pk_mul_f32 v[8:9], v[8:9], v[24:25] op_sel_hi:[1,0]
	v_pk_mul_f32 v[10:11], v[10:11], v[24:25] op_sel_hi:[1,0]
	v_lshlrev_b32_e32 v40, 16, v138
	v_and_b32_e32 v41, 0xffff0000, v138
	v_lshlrev_b32_e32 v42, 16, v139
	v_and_b32_e32 v43, 0xffff0000, v139
	v_pk_mul_f32 v[8:9], v[112:113], v[8:9]
	v_pk_mul_f32 v[10:11], v[114:115], v[10:11]
	v_pk_mul_f32 v[8:9], v[8:9], v[40:41]
	v_pk_mul_f32 v[10:11], v[10:11], v[42:43]
	v_cvt_pk_bf16_f32 v8, v8, v9
	v_cvt_pk_bf16_f32 v9, v10, v11
	global_store_dwordx2 v[16:17], v[8:9], off offset:2272
	v_mov_b32_e32 v15, v183
	s_cmp_lg_u32 s98, 0
	s_cbranch_scc1 .Lp2_item_done
	s_cmp_lt_i32 s9, 3
	s_cbranch_scc1 .LBB0_579
	s_cmp_lt_i32 s9, 4
	s_cbranch_scc1 .LBB0_580
	s_cmp_lt_i32 s9, 5
	s_cbranch_scc1 .LBB0_581
	s_cmp_lg_u32 s9, 5
	s_cbranch_scc0 .LBB0_582
	s_cmp_eq_u32 s9, 6
	s_cselect_b64 vcc, -1, 0
	v_mov_b32_e32 v4, 0xba38b001
	v_mov_b32_e32 v5, 0xbab8b5c7
	v_cndmask_b32_e32 v12, v4, v5, vcc
	s_cbranch_execz .LBB0_583
	s_branch .LBB0_584
